# ffn_up halo-row LDS-DMA restricted to the 16 lanes that carry the two halo rows (was a full 64-lane piece with 6 redundant rows)
# speedup vs baseline: 1.0012x; 1.0012x over previous
; __device__ __forceinline__ int ltid() { int t = (int)threadIdx.x; asm volatile("" : "+v"(t)); return t; }
; #define ISSUE(k0, bf) do { char* A_ = lw + (bf) * BUF; \
;     _Pragma("unroll") for (int i_ = 0; i_ < 4; ++i_) { glds16(al.ptr(lrow + 32 * i_, (k0) + cg), A_ + i_ * 4096); glds16(bl.ptr(lrow + 32 * i_, (k0) + cg), A_ + ABYTES + i_ * 4096); } \
;     if (HALO) { if (wid == 0) glds16(gh + (k0), A_ + 16384); } } while (0)
; template <bool HALO, class AL, class BL>
; __device__ __forceinline__ void gemm_core(f32x16 (&acc)[2][2], f32x16& hacc, const AL& al, const BL& bl, int K, char* lds,
;                                           const u16* halo0, const u16* halo1, int brow0, int brow1) {
;     ...
;   const int tid = ltid(), lane = tid & 63, wid = tid >> 6, wr = wid >> 1, r32 = lane & 31, hi = lane >> 5;
;   const int lrow = tid >> 3, cg = ((tid & 7) ^ ((lrow >> 1) & 7)) * 8;
;   const u16* gh = nullptr;
;   if (HALO) { const int c = ((lane & 7) ^ ((lane >> 4) & 7)) * 8; gh = ((lane < 8) ? halo0 : halo1) + c; }
;   char* lw = lds + tid * 16;
;     ...
;   const int sa = ((wr * 64 + r32) >> 1) & 7, sb0 = ((brow0 + r32) >> 1) & 7, sb1 = ((brow1 + r32) >> 1) & 7, sh = (r32 >> 1) & 7;
;   const int oa = (wr * 64 + r32) * 128, ob0 = ABYTES + (brow0 + r32) * 128, ob1 = ABYTES + (brow1 + r32) * 128, oh = (128 + r32) * 128;
;   __syncthreads();
;   ISSUE(0, 0);
; __device__ __forceinline__ void phase_ffn_up(const P& p, int layer, char* lds) {
;     ...
;   for (int it = 0; tile_at(it, 256, 44, tm, tn); ++it) {
;     f32x16 acc[2][2] = {}; f32x16 hacc = {};
;     const long r0 = (long)tm * 128;
;     const bool top0 = (r0 % SEQ) == 0, bot0 = ((r0 + 128) % SEQ) == 0;
;     LdBf al{xb + r0 * DM, DM}; LdBsplit bl{wt, DM, tn * 64};
;     const u16* zr = (const u16*)(p.ws + OFF_ZERO);
;     const u16* h0 = top0 ? zr : xb + (r0 - 1) * DM; const u16* h1 = bot0 ? zr : xb + (r0 + 128) * DM;
;     gemm_core<true>(acc, hacc, al, bl, DM, lds, h0, h1, wc * 32, 64 + wc * 32);
.LBB0_166:
	v_readlane_b32 s7, v254, 55
	s_add_i32 s7, s6, s7
	s_mul_hi_u32 s8, s7, 0xba2e8ba3
	s_lshr_b32 s8, s8, 8
	s_lshl_b32 s42, s8, 3
	s_and_b32 s6, s6, 7
	s_mulk_i32 s8, 0xfea0
	s_or_b32 s92, s42, s6
	s_add_i32 s8, s8, s7
	s_lshl_b64 s[6:7], s[92:93], 7
	s_and_b32 s64, s92, 63
	v_mov_b32_e32 v0, v229
	s_add_u32 s84, s6, 0x80
	s_addc_u32 s85, s7, 0
	v_lshrrev_b32_e32 v1, 4, v0
	s_and_b32 s72, s84, 0x1f80
	s_lshl_b64 s[6:7], s[92:93], 18
	v_xor_b32_e32 v1, v1, v0
	v_lshl_add_u32 v102, v0, 4, 0
	s_add_u32 s6, s69, s6
	v_ashrrev_i32_e32 v2, 3, v0
	v_lshlrev_b32_e32 v1, 4, v1
	v_readfirstlane_b32 s42, v102
	s_addc_u32 s7, s3, s7
	s_lshl_b32 s8, s8, 3
	v_and_b32_e32 v200, 0x70, v1
	v_ashrrev_i32_e32 v3, 31, v2
	s_mov_b32 m0, s42
	v_add_u32_e32 v1, 0xac0, v2
	v_cmp_gt_i32_e64 s[42:43], 64, v2
	s_andn2_b32 s8, s8, 63
	v_lshl_add_u64 v[4:5], s[6:7], 0, v[200:201]
	v_lshlrev_b64 v[6:7], 11, v[2:3]
	v_cndmask_b32_e64 v1, v1, v2, s[42:43]
	v_lshl_add_u64 v[82:83], v[4:5], 0, v[6:7]
	v_add_u32_e32 v6, s8, v1
	v_ashrrev_i32_e32 v7, 31, v6
	v_add_u32_e32 v123, 0x4400, v102
	v_lshlrev_b64 v[6:7], 11, v[6:7]
	v_lshl_add_u64 v[6:7], s[80:81], 0, v[6:7]
	v_readfirstlane_b32 s42, v123
	v_add_u32_e32 v124, 0x1000, v102
	s_waitcnt lgkmcnt(0)
	s_barrier
	global_load_lds_dwordx4 v[82:83], off
	v_lshl_add_u64 v[84:85], v[6:7], 0, v[200:201]
	s_mov_b32 m0, s42
	v_readfirstlane_b32 s42, v124
	global_load_lds_dwordx4 v[84:85], off
	v_add_u32_e32 v6, 32, v2
	s_mov_b32 m0, s42
	v_add_u32_e32 v1, 0xae0, v2
	v_cmp_gt_i32_e64 s[42:43], 32, v2
	v_ashrrev_i32_e32 v7, 31, v6
	s_waitcnt vmcnt(2)
	v_lshlrev_b64 v[8:9], 11, v[6:7]
	v_cndmask_b32_e64 v1, v1, v6, s[42:43]
	v_add_u32_e32 v6, s8, v1
	v_ashrrev_i32_e32 v7, 31, v6
	v_lshlrev_b64 v[6:7], 11, v[6:7]
	v_add_u32_e32 v125, 0x5400, v102
	v_lshl_add_u64 v[86:87], v[4:5], 0, v[8:9]
	v_lshl_add_u64 v[6:7], s[80:81], 0, v[6:7]
	v_readfirstlane_b32 s42, v125
	v_add_u32_e32 v126, 0x2000, v102
	global_load_lds_dwordx4 v[86:87], off
	v_lshl_add_u64 v[88:89], v[6:7], 0, v[200:201]
	s_mov_b32 m0, s42
	v_readfirstlane_b32 s42, v126
	global_load_lds_dwordx4 v[88:89], off
	v_add_u32_e32 v6, 64, v2
	s_mov_b32 m0, s42
	v_add_u32_e32 v1, 0xb00, v2
	v_cmp_gt_i32_e64 s[42:43], 0, v2
	v_ashrrev_i32_e32 v7, 31, v6
	v_lshlrev_b64 v[8:9], 11, v[6:7]
	v_cndmask_b32_e64 v1, v1, v6, s[42:43]
	v_add_u32_e32 v6, s8, v1
	v_ashrrev_i32_e32 v7, 31, v6
	v_lshlrev_b64 v[6:7], 11, v[6:7]
	v_add_u32_e32 v127, 0x6400, v102
	v_lshl_add_u64 v[90:91], v[4:5], 0, v[8:9]
	v_lshl_add_u64 v[6:7], s[80:81], 0, v[6:7]
	v_readfirstlane_b32 s42, v127
	v_add_u32_e32 v128, 0x3000, v102
	global_load_lds_dwordx4 v[90:91], off
	v_lshl_add_u64 v[92:93], v[6:7], 0, v[200:201]
	s_mov_b32 m0, s42
	v_readfirstlane_b32 s42, v128
	global_load_lds_dwordx4 v[92:93], off
	s_mov_b32 m0, s42
	s_movk_i32 s42, 0xffe0
	v_add_u32_e32 v6, 0x60, v2
	v_add_u32_e32 v1, 0xb20, v2
	v_cmp_gt_i32_e64 s[42:43], s42, v2
	v_ashrrev_i32_e32 v7, 31, v6
	v_lshlrev_b64 v[8:9], 11, v[6:7]
	v_cndmask_b32_e64 v1, v1, v6, s[42:43]
	v_add_u32_e32 v2, s8, v1
	v_ashrrev_i32_e32 v3, 31, v2
	v_lshlrev_b64 v[2:3], 11, v[2:3]
	v_add_u32_e32 v129, 0x7400, v102
	v_lshl_add_u64 v[94:95], v[4:5], 0, v[8:9]
	v_lshl_add_u64 v[2:3], s[80:81], 0, v[2:3]
	v_readfirstlane_b32 s42, v129
	global_load_lds_dwordx4 v[94:95], off
	v_lshl_add_u64 v[96:97], v[2:3], 0, v[200:201]
	s_mov_b32 m0, s42
	s_add_u32 s6, s6, 0xfffff800
	global_load_lds_dwordx4 v[96:97], off
	s_addc_u32 s7, s7, -1
	s_cmp_eq_u32 s64, 0
	s_cselect_b32 s64, s40, s6
	s_cselect_b32 s42, s41, s7
	s_lshl_b64 s[6:7], s[84:85], 11
	s_add_u32 s6, s69, s6
	s_mov_b32 s73, s93
	s_addc_u32 s7, s3, s7
	s_cmp_eq_u64 s[72:73], 0
	s_cselect_b32 s7, s41, s7
	v_and_b32_e32 v1, 63, v0
	v_bfe_u32 v2, v0, 4, 2
	s_cselect_b32 s6, s40, s6
	v_bitop3_b32 v4, v2, v0, 7 bitop3:0x78
	v_mov_b32_e32 v2, s7
	v_mov_b32_e32 v3, s42
	v_cmp_gt_u32_e64 s[42:43], 8, v1
	v_mov_b32_e32 v5, s64
	v_lshlrev_b32_e32 v200, 4, v4
	v_cndmask_b32_e64 v3, v2, v3, s[42:43]
	v_mov_b32_e32 v2, s6
	v_cndmask_b32_e64 v2, v2, v5, s[42:43]
	v_lshl_add_u64 v[98:99], v[2:3], 0, v[200:201]
	v_cmp_gt_u32_e64 s[42:43], 16, v0
	s_and_saveexec_b64 s[6:7], s[42:43]
	s_cbranch_execz .LBB0_168
	v_add_u32_e32 v2, 0x4000, v102
	s_nop 0
	v_readfirstlane_b32 s64, v2
	s_mov_b32 m0, s64
	s_nop 0
	global_load_lds_dwordx4 v[98:99], off
